# DSA attention: per-lane half row sums through the KV loop as in the differential loop, halves added once in the item epilogue
# baseline (speedup 1.0000x reference)
; __device__ __forceinline__ void dsa_attn_item(CParams& p, LAS unsigned char* lds, int b, int qb, int tid_in, int wave) {
;     ...
;     const float inv = 1.f / l_run;
; #pragma unroll
;     for (int d = 0; d < 4; ++d)
; #pragma unroll
;         for (int i = 0; i < 16; ++i) { const int dv = 32 * d + (i & 3) + 8 * (i >> 2) + 4 * hh;
;             y[(size_t)(tb0 + q0 + r) * D + 512 + hd * 128 + dv] = (h16)(o[d][i] * inv); }
.LBB0_399:
	ds_bpermute_b32 v2, v185, v198
	s_waitcnt lgkmcnt(0)
	v_add_f32_e32 v198, v198, v2
	v_div_scale_f32 v0, s[4:5], v198, v198, 1.0
	v_rcp_f32_e32 v2, v0
	v_ashrrev_i32_e32 v145, 31, v144
	v_mov_b32_e32 v147, v1
	s_add_i32 s82, s82, 1
	v_fma_f32 v3, -v0, v2, 1.0
	v_fmac_f32_e32 v2, v3, v2
	v_div_scale_f32 v3, vcc, 1.0, v198, 1.0
	v_mul_f32_e32 v4, v3, v2
	v_fma_f32 v5, -v0, v4, v3
	v_fmac_f32_e32 v4, v5, v2
	v_fma_f32 v0, -v0, v4, v3
	v_div_fmas_f32 v0, v0, v2, v4
	v_div_fixup_f32 v0, v0, v198, 1.0
	v_lshlrev_b64 v[2:3], 11, v[144:145]
	v_lshl_add_u64 v[2:3], v[138:139], 0, v[2:3]
	v_mul_f32_e32 v4, v64, v0
	v_mul_f32_e32 v6, v65, v0
	v_mul_f32_e32 v5, v66, v0
	v_mul_f32_e32 v7, v67, v0
	v_lshl_add_u64 v[2:3], v[146:147], 1, v[2:3]
	v_cvt_pk_f16_f32 v5, v5, v7
	v_cvt_pk_f16_f32 v4, v4, v6
	global_store_dwordx2 v[2:3], v[4:5], off
	v_mul_f32_e32 v4, v68, v0
	v_mul_f32_e32 v6, v69, v0
	v_mul_f32_e32 v5, v70, v0
	v_mul_f32_e32 v7, v71, v0
	v_cvt_pk_f16_f32 v5, v5, v7
	v_cvt_pk_f16_f32 v4, v4, v6
	global_store_dwordx2 v[2:3], v[4:5], off offset:16
	v_mul_f32_e32 v4, v72, v0
	v_mul_f32_e32 v6, v73, v0
	v_mul_f32_e32 v5, v74, v0
	v_mul_f32_e32 v7, v75, v0
	v_cvt_pk_f16_f32 v5, v5, v7
	v_cvt_pk_f16_f32 v4, v4, v6
	global_store_dwordx2 v[2:3], v[4:5], off offset:32
	v_mul_f32_e32 v4, v76, v0
	v_mul_f32_e32 v6, v77, v0
	v_mul_f32_e32 v5, v78, v0
	v_mul_f32_e32 v7, v79, v0
	v_cvt_pk_f16_f32 v5, v5, v7
	v_cvt_pk_f16_f32 v4, v4, v6
	global_store_dwordx2 v[2:3], v[4:5], off offset:48
	v_mul_f32_e32 v4, v48, v0
	v_mul_f32_e32 v6, v49, v0
	v_mul_f32_e32 v5, v50, v0
	v_mul_f32_e32 v7, v51, v0
	v_cvt_pk_f16_f32 v5, v5, v7
	v_cvt_pk_f16_f32 v4, v4, v6
	global_store_dwordx2 v[2:3], v[4:5], off offset:64
	v_mul_f32_e32 v4, v52, v0
	v_mul_f32_e32 v6, v53, v0
	v_mul_f32_e32 v5, v54, v0
	v_mul_f32_e32 v7, v55, v0
	v_cvt_pk_f16_f32 v5, v5, v7
	v_cvt_pk_f16_f32 v4, v4, v6
	global_store_dwordx2 v[2:3], v[4:5], off offset:80
	v_mul_f32_e32 v4, v56, v0
	v_mul_f32_e32 v6, v57, v0
	v_mul_f32_e32 v5, v58, v0
	v_mul_f32_e32 v7, v59, v0
	v_cvt_pk_f16_f32 v5, v5, v7
	v_cvt_pk_f16_f32 v4, v4, v6
	global_store_dwordx2 v[2:3], v[4:5], off offset:96
	v_mul_f32_e32 v4, v60, v0
	v_mul_f32_e32 v6, v61, v0
	v_mul_f32_e32 v5, v62, v0
	v_mul_f32_e32 v7, v63, v0
	v_cvt_pk_f16_f32 v5, v5, v7
	v_cvt_pk_f16_f32 v4, v4, v6
	global_store_dwordx2 v[2:3], v[4:5], off offset:112
	v_mul_f32_e32 v4, v32, v0
	v_mul_f32_e32 v6, v33, v0
	v_mul_f32_e32 v5, v34, v0
	v_mul_f32_e32 v7, v35, v0
	v_cvt_pk_f16_f32 v5, v5, v7
	v_cvt_pk_f16_f32 v4, v4, v6
	global_store_dwordx2 v[2:3], v[4:5], off offset:128
	v_mul_f32_e32 v4, v36, v0
	v_mul_f32_e32 v6, v37, v0
	v_mul_f32_e32 v5, v38, v0
	v_mul_f32_e32 v7, v39, v0
	v_cvt_pk_f16_f32 v5, v5, v7
	v_cvt_pk_f16_f32 v4, v4, v6
	global_store_dwordx2 v[2:3], v[4:5], off offset:144
	v_mul_f32_e32 v4, v40, v0
	v_mul_f32_e32 v6, v41, v0
	v_mul_f32_e32 v5, v42, v0
	v_mul_f32_e32 v7, v43, v0
	v_cvt_pk_f16_f32 v5, v5, v7
	v_cvt_pk_f16_f32 v4, v4, v6
	global_store_dwordx2 v[2:3], v[4:5], off offset:160
	v_mul_f32_e32 v4, v44, v0
	v_mul_f32_e32 v6, v45, v0
	v_mul_f32_e32 v5, v46, v0
	v_mul_f32_e32 v7, v47, v0
	v_cvt_pk_f16_f32 v5, v5, v7
	v_cvt_pk_f16_f32 v4, v4, v6
	global_store_dwordx2 v[2:3], v[4:5], off offset:176
	v_mul_f32_e32 v4, v16, v0
	v_mul_f32_e32 v6, v17, v0
	v_mul_f32_e32 v5, v18, v0
	v_mul_f32_e32 v7, v19, v0
	v_cvt_pk_f16_f32 v5, v5, v7
	v_cvt_pk_f16_f32 v4, v4, v6
	global_store_dwordx2 v[2:3], v[4:5], off offset:192
	v_mul_f32_e32 v4, v20, v0
	v_mul_f32_e32 v6, v21, v0
	v_mul_f32_e32 v5, v22, v0
	v_mul_f32_e32 v7, v23, v0
	v_cvt_pk_f16_f32 v5, v5, v7
	v_cvt_pk_f16_f32 v4, v4, v6
	global_store_dwordx2 v[2:3], v[4:5], off offset:208
	v_mul_f32_e32 v4, v24, v0
	v_mul_f32_e32 v6, v25, v0
	v_mul_f32_e32 v5, v26, v0
	v_mul_f32_e32 v7, v27, v0
	v_cvt_pk_f16_f32 v5, v5, v7
	v_cvt_pk_f16_f32 v4, v4, v6
	global_store_dwordx2 v[2:3], v[4:5], off offset:224
	v_mul_f32_e32 v4, v28, v0
	v_mul_f32_e32 v6, v29, v0
	v_mul_f32_e32 v5, v30, v0
	v_mul_f32_e32 v0, v31, v0
	v_cvt_pk_f16_f32 v5, v5, v0
	v_cvt_pk_f16_f32 v4, v4, v6
	s_cmp_eq_u32 s82, 4
	global_store_dwordx2 v[2:3], v[4:5], off offset:240
	s_barrier
	s_cbranch_scc0 .LBB0_400
	s_getpc_b64 s[98:99]

; __device__ __forceinline__ void dsa_attn_item(CParams& p, LAS unsigned char* lds, int b, int qb, int tid_in, int wave) {
;     ...
; #pragma unroll
;                 for (int i = 0; i < 16; ++i) { const float e = __builtin_amdgcn_exp2f(sc[i] - msafe); sc[i] = e; ls += e; }
;                 ls += __shfl_xor(ls, 32);
;                 l_run = l_run * alpha + ls; m_run = m_new;
.LdsaA_s0_t2:
	v_pk_add_f32 v[236:237], v[236:237], v[90:91] op_sel_hi:[1,0] neg_lo:[0,1] neg_hi:[0,1]
	v_pk_add_f32 v[238:239], v[238:239], v[90:91] op_sel_hi:[1,0] neg_lo:[0,1] neg_hi:[0,1]
	v_pk_add_f32 v[240:241], v[240:241], v[90:91] op_sel_hi:[1,0] neg_lo:[0,1] neg_hi:[0,1]
	v_pk_add_f32 v[242:243], v[242:243], v[90:91] op_sel_hi:[1,0] neg_lo:[0,1] neg_hi:[0,1]
	v_pk_add_f32 v[244:245], v[244:245], v[90:91] op_sel_hi:[1,0] neg_lo:[0,1] neg_hi:[0,1]
	v_pk_add_f32 v[246:247], v[246:247], v[90:91] op_sel_hi:[1,0] neg_lo:[0,1] neg_hi:[0,1]
	v_pk_add_f32 v[248:249], v[248:249], v[90:91] op_sel_hi:[1,0] neg_lo:[0,1] neg_hi:[0,1]
	v_pk_add_f32 v[250:251], v[250:251], v[90:91] op_sel_hi:[1,0] neg_lo:[0,1] neg_hi:[0,1]
	v_exp_f32_e32 v236, v236
	v_exp_f32_e32 v237, v237
	v_exp_f32_e32 v238, v238
	v_exp_f32_e32 v239, v239
	v_exp_f32_e32 v240, v240
	v_exp_f32_e32 v241, v241
	v_exp_f32_e32 v242, v242
	v_exp_f32_e32 v243, v243
	v_exp_f32_e32 v244, v244
	v_exp_f32_e32 v245, v245
	v_exp_f32_e32 v246, v246
	v_exp_f32_e32 v247, v247
	v_exp_f32_e32 v248, v248
	v_exp_f32_e32 v249, v249
	v_exp_f32_e32 v250, v250
	v_exp_f32_e32 v251, v251
	v_pk_add_f32 v[92:93], v[236:237], v[238:239]
	v_pk_add_f32 v[92:93], v[92:93], v[240:241]
	v_pk_add_f32 v[92:93], v[92:93], v[242:243]
	v_pk_add_f32 v[92:93], v[92:93], v[244:245]
	v_pk_add_f32 v[92:93], v[92:93], v[246:247]
	v_pk_add_f32 v[92:93], v[92:93], v[248:249]
	v_pk_add_f32 v[92:93], v[92:93], v[250:251]
	s_nop 0
	v_add_f32_e32 v92, v92, v93
	v_cvt_pk_f16_f32 v232, v236, v237
	v_cvt_pk_f16_f32 v233, v238, v239
	v_cvt_pk_f16_f32 v234, v240, v241
	v_cvt_pk_f16_f32 v235, v242, v243
	v_cvt_pk_f16_f32 v228, v244, v245
	v_cvt_pk_f16_f32 v229, v246, v247
	v_cvt_pk_f16_f32 v230, v248, v249
	v_cvt_pk_f16_f32 v231, v250, v251
	s_cmp_lg_u32 s101, 0
	s_cbranch_scc1 .LdsaA_s0_ok
	v_cmp_nge_f32_e32 vcc, 0x43800000, v92
	s_cbranch_vccz .LdsaA_s0_ok
	s_mov_b32 s100, 0
	s_mov_b32 s101, 1
	s_branch .LdsaA_s0_top
